# Fourier latent items (phases 6 and 8): twiddle fragments loaded once per workgroup instead of per item (removes a global-load round trip before each item's MFMAs)
# baseline (speedup 1.0000x reference)
.LBB0_595:
	s_cmpk_gt_i32 s2, 0x7ff
	s_cbranch_scc1 .LBB0_602
	v_bfe_u32 v4, v146, 4, 2
	v_lshlrev_b32_e32 v0, 4, v4
	v_mov_b32_e32 v1, 0
	v_lshlrev_b32_e32 v6, 4, v195
	v_lshl_add_u64 v[2:3], s[34:35], 0, v[0:1]
	v_add_u32_e32 v5, 0, v0
	v_or_b32_e32 v0, v6, v181
	s_movk_i32 s0, 0x200
	v_lshlrev_b32_e32 v0, 8, v0
	v_cmp_gt_u32_e64 s[6:7], s0, v146
	v_lshlrev_b32_e32 v4, 2, v4
	v_lshl_add_u64 v[2:3], v[2:3], 0, v[0:1]
	s_mov_b64 s[0:1], 0x3140000
	v_mul_u32_u24_e32 v0, 0x110, v181
	v_lshlrev_b32_e32 v7, 5, v195
	v_lshl_add_u64 v[2:3], v[2:3], 0, s[0:1]
	s_and_saveexec_b64 s[16:17], s[6:7]
	global_load_dwordx4 v[124:127], v[2:3], off
	global_load_dwordx4 v[128:131], v[2:3], off offset:64
	global_load_dwordx4 v[132:135], v[2:3], off offset:128
	global_load_dwordx4 v[136:139], v[2:3], off offset:192
	s_or_b64 exec, exec, s[16:17]
	s_movk_i32 s3, 0x110
	v_bitop3_b32 v6, v6, 63, v181 bitop3:0xc8
	v_and_b32_e32 v7, 0x80, v7
	v_add_u32_e32 v8, 0xfffffe00, v146
	v_lshlrev_b32_e32 v9, 1, v146
	s_mov_b32 s4, 0xffff0000
	v_add_u32_e32 v10, v5, v0
	v_lshlrev_b32_e32 v4, 1, v4
	s_mov_b32 s5, s2
	s_branch .LBB0_598

.LBB0_598:
	s_lshl_b32 s0, s5, 4
	s_and_b32 s10, s0, 0xffffffc0
	s_lshl_b32 s0, s5, 8
	s_and_b32 s11, s0, 0x300
	s_addk_i32 s10, 0x2000
	s_lshl_b32 s0, s11, 1
	s_add_u32 s0, s58, s0
	s_addc_u32 s1, s59, 0
	s_mov_b64 s[8:9], 0
	v_mov_b32_e32 v5, v9
	v_mov_b32_e32 v11, v101
	v_mov_b32_e32 v12, v8
	v_and_b32_e32 v13, 62, v5
	v_or_b32_e32 v14, s10, v13
	v_ashrrev_i32_e32 v15, 31, v14
	v_and_b32_e32 v22, 0x80, v11
	v_lshlrev_b64 v[14:15], 11, v[14:15]
	v_and_b32_e32 v23, 0x78, v11
	v_lshlrev_b32_e32 v0, 1, v22
	v_lshl_add_u64 v[14:15], s[0:1], 0, v[14:15]
	v_lshl_add_u64 v[14:15], v[14:15], 0, v[0:1]
	v_lshlrev_b32_e32 v0, 1, v23
	v_lshl_add_u64 v[36:37], v[14:15], 0, v[0:1]
	global_load_dwordx4 v[14:17], v[36:37], off
	global_load_dwordx4 v[18:21], v[36:37], off offset:2048
	global_load_dwordx4 v[28:31], v[36:37], off offset:256
	global_load_dwordx4 v[32:35], v[36:37], off offset:2304
	v_mad_u32_u24 v0, v23, s3, 0
	v_lshlrev_b32_e32 v13, 1, v13
	v_add3_u32 v0, v0, v22, v13
	v_add_u32_e32 v13, 0x400, v0
	v_add_u32_e32 v26, 0x80, v0
	v_add_u32_e32 v27, 0x480, v0
	s_waitcnt vmcnt(3)
	v_and_b32_e32 v22, 0xffff, v14
	v_lshrrev_b32_e32 v14, 16, v14
	v_and_b32_e32 v23, 0xffff, v15
	v_lshrrev_b32_e32 v15, 16, v15
	v_and_b32_e32 v24, 0xffff, v16
	v_lshrrev_b32_e32 v16, 16, v16
	v_and_b32_e32 v25, 0xffff, v17
	v_lshrrev_b32_e32 v17, 16, v17
	s_waitcnt vmcnt(2)
	v_lshl_or_b32 v22, v18, 16, v22
	v_and_or_b32 v14, v18, s4, v14
	v_lshl_or_b32 v18, v19, 16, v23
	v_and_or_b32 v15, v19, s4, v15
	v_lshl_or_b32 v19, v20, 16, v24
	v_and_or_b32 v16, v20, s4, v16
	v_lshl_or_b32 v20, v21, 16, v25
	v_and_or_b32 v17, v21, s4, v17
	ds_write2_b32 v0, v22, v14 offset1:68
	ds_write2_b32 v0, v18, v15 offset0:136 offset1:204
	ds_write2_b32 v13, v19, v16 offset0:16 offset1:84
	ds_write2_b32 v13, v20, v17 offset0:152 offset1:220
	s_waitcnt vmcnt(1)
	v_and_b32_e32 v38, 0xffff, v28
	v_lshrrev_b32_e32 v28, 16, v28
	v_and_b32_e32 v39, 0xffff, v29
	v_lshrrev_b32_e32 v29, 16, v29
	v_and_b32_e32 v40, 0xffff, v30
	v_lshrrev_b32_e32 v30, 16, v30
	v_and_b32_e32 v41, 0xffff, v31
	v_lshrrev_b32_e32 v31, 16, v31
	s_waitcnt vmcnt(0)
	v_lshl_or_b32 v38, v32, 16, v38
	v_and_or_b32 v28, v32, s4, v28
	v_lshl_or_b32 v32, v33, 16, v39
	v_and_or_b32 v29, v33, s4, v29
	v_lshl_or_b32 v33, v34, 16, v40
	v_and_or_b32 v30, v34, s4, v30
	v_lshl_or_b32 v34, v35, 16, v41
	v_and_or_b32 v31, v35, s4, v31
	ds_write2_b32 v26, v38, v28 offset1:68
	ds_write2_b32 v26, v32, v29 offset0:136 offset1:204
	ds_write2_b32 v27, v33, v30 offset0:16 offset1:84
	ds_write2_b32 v27, v34, v31 offset0:152 offset1:220
	s_waitcnt lgkmcnt(0)
	s_barrier
	s_and_saveexec_b64 s[0:1], s[6:7]
	s_cbranch_execz .LBB0_597
	ds_read_b128 v[16:19], v10
	ds_read_b128 v[24:27], v10 offset:64
	ds_read_b128 v[28:31], v10 offset:4352
	ds_read_b128 v[32:35], v10 offset:4416
	ds_read_b128 v[36:39], v10 offset:8704
	ds_read_b128 v[40:43], v10 offset:8768
	ds_read_b128 v[44:47], v10 offset:13056
	ds_read_b128 v[48:51], v10 offset:13120
	ds_read_b128 v[52:55], v10 offset:17408
	ds_read_b128 v[56:59], v10 offset:17472
	ds_read_b128 v[60:63], v10 offset:21760
	ds_read_b128 v[64:67], v10 offset:21824
	ds_read_b128 v[68:71], v10 offset:26112
	ds_read_b128 v[72:75], v10 offset:26176
	ds_read_b128 v[76:79], v10 offset:30464
	ds_read_b128 v[80:83], v10 offset:30528
	v_or_b32_e32 v0, s11, v7
	v_lshlrev_b32_e32 v0, 1, v0
	v_mov_b32_e32 v5, v1
	s_waitcnt lgkmcnt(14)
	v_mfma_f32_16x16x32_bf16 v[16:19], v[16:19], v[124:127], 0
	s_waitcnt lgkmcnt(13)
	v_mfma_f32_16x16x32_bf16 v[28:31], v[28:31], v[124:127], 0
	s_waitcnt lgkmcnt(11)
	v_mfma_f32_16x16x32_bf16 v[36:39], v[36:39], v[124:127], 0
	v_mfma_f32_16x16x32_bf16 v[16:19], v[24:27], v[128:131], v[16:19]
	v_mfma_f32_16x16x32_bf16 v[24:27], v[32:35], v[128:131], v[28:31]
	s_waitcnt lgkmcnt(10)
	v_mfma_f32_16x16x32_bf16 v[28:31], v[40:43], v[128:131], v[36:39]
	s_waitcnt lgkmcnt(9)
	v_mfma_f32_16x16x32_bf16 v[44:47], v[44:47], v[124:127], 0
	s_waitcnt lgkmcnt(8)
	v_mfma_f32_16x16x32_bf16 v[32:35], v[48:51], v[128:131], v[44:47]
	s_waitcnt lgkmcnt(7)
	v_mfma_f32_16x16x32_bf16 v[52:55], v[52:55], v[124:127], 0
	s_waitcnt lgkmcnt(6)
	v_mfma_f32_16x16x32_bf16 v[36:39], v[56:59], v[128:131], v[52:55]
	ds_read_b128 v[56:59], v10 offset:128
	s_waitcnt lgkmcnt(6)
	v_mfma_f32_16x16x32_bf16 v[60:63], v[60:63], v[124:127], 0
	s_waitcnt lgkmcnt(4)
	v_mfma_f32_16x16x32_bf16 v[68:71], v[68:71], v[124:127], 0
	s_waitcnt lgkmcnt(2)
	v_mfma_f32_16x16x32_bf16 v[12:15], v[76:79], v[124:127], 0
	v_mfma_f32_16x16x32_bf16 v[44:47], v[64:67], v[128:131], v[60:63]
	v_mfma_f32_16x16x32_bf16 v[52:55], v[72:75], v[128:131], v[68:71]
	s_waitcnt lgkmcnt(1)
	v_mfma_f32_16x16x32_bf16 v[12:15], v[80:83], v[128:131], v[12:15]
	ds_read_b128 v[20:23], v10 offset:4480
	ds_read_b128 v[60:63], v10 offset:192
	s_waitcnt lgkmcnt(2)
	v_mfma_f32_16x16x32_bf16 v[16:19], v[56:59], v[132:135], v[16:19]
	ds_read_b128 v[56:59], v10 offset:8832
	ds_read_b128 v[64:67], v10 offset:4544
	s_waitcnt lgkmcnt(3)
	v_mfma_f32_16x16x32_bf16 v[20:23], v[20:23], v[132:135], v[24:27]
	s_nop 2
	ds_read_b128 v[24:27], v10 offset:13184
	ds_read_b128 v[68:71], v10 offset:8896
	s_waitcnt lgkmcnt(3)
	v_mfma_f32_16x16x32_bf16 v[28:31], v[56:59], v[132:135], v[28:31]
	ds_read_b128 v[56:59], v10 offset:17536
	ds_read_b128 v[72:75], v10 offset:21888
	ds_read_b128 v[76:79], v10 offset:13248
	s_waitcnt lgkmcnt(4)
	v_mfma_f32_16x16x32_bf16 v[24:27], v[24:27], v[132:135], v[32:35]
	s_nop 2
	ds_read_b128 v[32:35], v10 offset:26240
	ds_read_b128 v[80:83], v10 offset:17600
	ds_read_b128 v[84:87], v10 offset:21952
	s_waitcnt lgkmcnt(5)
	v_mfma_f32_16x16x32_bf16 v[36:39], v[56:59], v[132:135], v[36:39]
	ds_read_b128 v[56:59], v10 offset:26304
	ds_read_b128 v[88:91], v10 offset:30592
	ds_read_b128 v[92:95], v10 offset:30656
	s_waitcnt lgkmcnt(7)
	v_mfma_f32_16x16x32_bf16 v[44:47], v[72:75], v[132:135], v[44:47]
	v_or_b32_e32 v72, s10, v6
	v_ashrrev_i32_e32 v73, 31, v72
	v_mfma_f32_16x16x32_bf16 v[16:19], v[60:63], v[136:139], v[16:19]
	s_waitcnt lgkmcnt(5)
	v_mfma_f32_16x16x32_bf16 v[32:35], v[32:35], v[132:135], v[52:55]
	s_nop 2
	v_lshlrev_b64 v[52:53], 11, v[72:73]
	v_lshl_add_u64 v[52:53], s[58:59], 0, v[52:53]
	s_waitcnt lgkmcnt(1)
	v_mfma_f32_16x16x32_bf16 v[12:15], v[88:91], v[132:135], v[12:15]
	v_lshl_add_u64 v[40:41], v[52:53], 0, v[0:1]
	v_lshl_add_u64 v[40:41], v[40:41], 0, v[4:5]
	v_cvt_pk_bf16_f32 v16, v16, v17
	v_cvt_pk_bf16_f32 v17, v18, v19
	global_store_dwordx2 v[40:41], v[16:17], off
	v_mfma_f32_16x16x32_bf16 v[16:19], v[64:67], v[136:139], v[20:23]
	s_waitcnt lgkmcnt(0)
	v_mfma_f32_16x16x32_bf16 v[12:15], v[92:95], v[136:139], v[12:15]
	s_nop 5
	v_cvt_pk_bf16_f32 v16, v16, v17
	v_cvt_pk_bf16_f32 v17, v18, v19
	global_store_dwordx2 v[40:41], v[16:17], off offset:32
	v_mfma_f32_16x16x32_bf16 v[16:19], v[68:71], v[136:139], v[28:31]
	v_cvt_pk_bf16_f32 v12, v12, v13
	v_cvt_pk_bf16_f32 v13, v14, v15
	global_store_dwordx2 v[40:41], v[12:13], off offset:224
	s_nop 4
	v_cvt_pk_bf16_f32 v16, v16, v17
	v_cvt_pk_bf16_f32 v17, v18, v19
	global_store_dwordx2 v[40:41], v[16:17], off offset:64
	v_mfma_f32_16x16x32_bf16 v[16:19], v[76:79], v[136:139], v[24:27]
	s_nop 7
	v_cvt_pk_bf16_f32 v16, v16, v17
	v_cvt_pk_bf16_f32 v17, v18, v19
	global_store_dwordx2 v[40:41], v[16:17], off offset:96
	v_mfma_f32_16x16x32_bf16 v[16:19], v[80:83], v[136:139], v[36:39]
	s_nop 7
	v_cvt_pk_bf16_f32 v16, v16, v17
	v_cvt_pk_bf16_f32 v17, v18, v19
	global_store_dwordx2 v[40:41], v[16:17], off offset:128
	v_mfma_f32_16x16x32_bf16 v[16:19], v[84:87], v[136:139], v[44:47]
	s_nop 7
	v_cvt_pk_bf16_f32 v16, v16, v17
	v_cvt_pk_bf16_f32 v17, v18, v19
	global_store_dwordx2 v[40:41], v[16:17], off offset:160
	v_mfma_f32_16x16x32_bf16 v[16:19], v[56:59], v[136:139], v[32:35]
	s_nop 7
	v_cvt_pk_bf16_f32 v16, v16, v17
	v_cvt_pk_bf16_f32 v17, v18, v19
	global_store_dwordx2 v[40:41], v[16:17], off offset:192
	s_branch .LBB0_597

.LBB0_755:
	v_readlane_b32 s0, v254, 10
	s_cmp_lt_i32 s2, s0
	s_cbranch_scc1 .LBB0_763
	s_cmpk_gt_i32 s97, 0x7ff
	s_barrier
	s_cbranch_scc1 .LBB0_763
	v_bfe_u32 v4, v146, 4, 2
	v_lshlrev_b32_e32 v0, 4, v4
	v_mov_b32_e32 v1, 0
	v_and_or_b32 v6, v101, 48, v181
	s_movk_i32 s0, 0x100
	v_lshl_add_u64 v[2:3], s[34:35], 0, v[0:1]
	v_add_u32_e32 v5, 0, v0
	v_lshlrev_b32_e32 v0, 8, v6
	v_cmp_gt_u32_e64 s[8:9], s0, v146
	v_lshlrev_b32_e32 v4, 2, v4
	v_lshl_add_u64 v[2:3], v[2:3], 0, v[0:1]
	s_mov_b64 s[0:1], 0x3148000
	v_mul_u32_u24_e32 v0, 0x110, v181
	v_lshl_add_u64 v[2:3], v[2:3], 0, s[0:1]
	s_and_saveexec_b64 s[16:17], s[8:9]
	global_load_dwordx4 v[124:127], v[2:3], off
	global_load_dwordx4 v[128:131], v[2:3], off offset:64
	global_load_dwordx4 v[132:135], v[2:3], off offset:128
	global_load_dwordx4 v[136:139], v[2:3], off offset:192
	s_or_b64 exec, exec, s[16:17]
	s_movk_i32 s3, 0x110
	v_lshlrev_b32_e32 v6, 6, v6
	v_add_u32_e32 v7, 0xfffffe00, v146
	v_lshlrev_b32_e32 v8, 1, v146
	s_mov_b32 s4, 0x20000
	s_mov_b32 s5, 0xffff0000
	v_lshlrev_b32_e32 v4, 1, v4
	v_add_u32_e32 v9, v5, v0
	s_branch .LBB0_759

.LBB0_759:
	s_lshl_b32 s1, s97, 4
	s_bfe_u32 s0, s97, 0x60002
	s_and_b32 s1, s1, 0xfffff000
	s_or_b32 s6, s1, s0
	s_lshl_b32 s0, s97, 9
	s_addk_i32 s6, 0x2000
	s_and_b32 s0, s0, 0x600
	s_add_u32 s0, s58, s0
	s_addc_u32 s1, s59, 0
	s_mov_b64 s[10:11], 0
	v_mov_b32_e32 v5, v8
	v_mov_b32_e32 v10, v101
	v_mov_b32_e32 v11, v7
	v_and_b32_e32 v20, 62, v5
	v_lshl_or_b32 v12, v20, 6, s6
	v_ashrrev_i32_e32 v13, 31, v12
	v_and_b32_e32 v21, 0x80, v10
	v_lshlrev_b64 v[12:13], 11, v[12:13]
	v_and_b32_e32 v22, 0x78, v10
	v_lshlrev_b32_e32 v0, 1, v21
	v_lshl_add_u64 v[12:13], s[0:1], 0, v[12:13]
	v_lshl_add_u64 v[12:13], v[12:13], 0, v[0:1]
	v_lshlrev_b32_e32 v0, 1, v22
	v_lshl_add_u64 v[36:37], v[12:13], 0, v[0:1]
	v_add_co_u32_e32 v38, vcc, s4, v36
	v_mad_u32_u24 v0, v22, s3, 0
	s_nop 0
	v_addc_co_u32_e32 v39, vcc, 0, v37, vcc
	global_load_dwordx4 v[12:15], v[36:37], off
	global_load_dwordx4 v[16:19], v[38:39], off
	global_load_dwordx4 v[28:31], v[36:37], off offset:256
	global_load_dwordx4 v[32:35], v[38:39], off offset:256
	v_lshlrev_b32_e32 v20, 1, v20
	v_add3_u32 v0, v0, v21, v20
	v_add_u32_e32 v20, 0x400, v0
	v_add_u32_e32 v26, 0x80, v0
	v_add_u32_e32 v27, 0x480, v0
	s_waitcnt vmcnt(3)
	v_and_b32_e32 v21, 0xffff, v12
	v_lshrrev_b32_e32 v12, 16, v12
	v_and_b32_e32 v22, 0xffff, v13
	v_lshrrev_b32_e32 v13, 16, v13
	v_and_b32_e32 v23, 0xffff, v14
	v_lshrrev_b32_e32 v14, 16, v14
	v_and_b32_e32 v24, 0xffff, v15
	v_lshrrev_b32_e32 v15, 16, v15
	s_waitcnt vmcnt(2)
	v_lshl_or_b32 v21, v16, 16, v21
	v_and_or_b32 v12, v16, s5, v12
	v_lshl_or_b32 v16, v17, 16, v22
	v_and_or_b32 v13, v17, s5, v13
	v_lshl_or_b32 v17, v18, 16, v23
	v_and_or_b32 v14, v18, s5, v14
	v_lshl_or_b32 v18, v19, 16, v24
	v_and_or_b32 v15, v19, s5, v15
	ds_write2_b32 v0, v21, v12 offset1:68
	ds_write2_b32 v0, v16, v13 offset0:136 offset1:204
	ds_write2_b32 v20, v17, v14 offset0:16 offset1:84
	ds_write2_b32 v20, v18, v15 offset0:152 offset1:220
	s_waitcnt vmcnt(1)
	v_and_b32_e32 v40, 0xffff, v28
	v_lshrrev_b32_e32 v28, 16, v28
	v_and_b32_e32 v41, 0xffff, v29
	v_lshrrev_b32_e32 v29, 16, v29
	v_and_b32_e32 v42, 0xffff, v30
	v_lshrrev_b32_e32 v30, 16, v30
	v_and_b32_e32 v43, 0xffff, v31
	v_lshrrev_b32_e32 v31, 16, v31
	s_waitcnt vmcnt(0)
	v_lshl_or_b32 v40, v32, 16, v40
	v_and_or_b32 v28, v32, s5, v28
	v_lshl_or_b32 v32, v33, 16, v41
	v_and_or_b32 v29, v33, s5, v29
	v_lshl_or_b32 v33, v34, 16, v42
	v_and_or_b32 v30, v34, s5, v30
	v_lshl_or_b32 v34, v35, 16, v43
	v_and_or_b32 v31, v35, s5, v31
	ds_write2_b32 v26, v40, v28 offset1:68
	ds_write2_b32 v26, v32, v29 offset0:136 offset1:204
	ds_write2_b32 v27, v33, v30 offset0:16 offset1:84
	ds_write2_b32 v27, v34, v31 offset0:152 offset1:220
	s_waitcnt lgkmcnt(0)
	s_barrier
	s_and_saveexec_b64 s[10:11], s[8:9]
	s_cbranch_execz .LBB0_758
	ds_read_b128 v[14:17], v9
	ds_read_b128 v[22:25], v9 offset:64
	ds_read_b128 v[26:29], v9 offset:4352
	ds_read_b128 v[30:33], v9 offset:4416
	ds_read_b128 v[34:37], v9 offset:8704
	ds_read_b128 v[38:41], v9 offset:8768
	ds_read_b128 v[42:45], v9 offset:13056
	ds_read_b128 v[46:49], v9 offset:13120
	ds_read_b128 v[50:53], v9 offset:17408
	ds_read_b128 v[54:57], v9 offset:17472
	ds_read_b128 v[58:61], v9 offset:21760
	ds_read_b128 v[62:65], v9 offset:21824
	ds_read_b128 v[66:69], v9 offset:26112
	ds_read_b128 v[70:73], v9 offset:26176
	ds_read_b128 v[74:77], v9 offset:30464
	ds_read_b128 v[78:81], v9 offset:30528
	v_or_b32_e32 v88, s6, v6
	v_mov_b32_e32 v5, v1
	v_ashrrev_i32_e32 v89, 31, v88
	v_lshl_add_u64 v[86:87], s[0:1], 0, v[4:5]
	s_waitcnt lgkmcnt(14)
	v_mfma_f32_16x16x32_bf16 v[14:17], v[14:17], v[124:127], 0
	s_waitcnt lgkmcnt(13)
	v_mfma_f32_16x16x32_bf16 v[26:29], v[26:29], v[124:127], 0
	s_waitcnt lgkmcnt(11)
	v_mfma_f32_16x16x32_bf16 v[34:37], v[34:37], v[124:127], 0
	v_mfma_f32_16x16x32_bf16 v[14:17], v[22:25], v[128:131], v[14:17]
	v_mfma_f32_16x16x32_bf16 v[22:25], v[30:33], v[128:131], v[26:29]
	s_waitcnt lgkmcnt(10)
	v_mfma_f32_16x16x32_bf16 v[26:29], v[38:41], v[128:131], v[34:37]
	s_waitcnt lgkmcnt(9)
	v_mfma_f32_16x16x32_bf16 v[42:45], v[42:45], v[124:127], 0
	s_waitcnt lgkmcnt(8)
	v_mfma_f32_16x16x32_bf16 v[30:33], v[46:49], v[128:131], v[42:45]
	s_waitcnt lgkmcnt(7)
	v_mfma_f32_16x16x32_bf16 v[50:53], v[50:53], v[124:127], 0
	s_waitcnt lgkmcnt(6)
	v_mfma_f32_16x16x32_bf16 v[34:37], v[54:57], v[128:131], v[50:53]
	ds_read_b128 v[54:57], v9 offset:128
	s_waitcnt lgkmcnt(6)
	v_mfma_f32_16x16x32_bf16 v[58:61], v[58:61], v[124:127], 0
	s_waitcnt lgkmcnt(4)
	v_mfma_f32_16x16x32_bf16 v[66:69], v[66:69], v[124:127], 0
	s_waitcnt lgkmcnt(2)
	v_mfma_f32_16x16x32_bf16 v[10:13], v[74:77], v[124:127], 0
	v_mfma_f32_16x16x32_bf16 v[42:45], v[62:65], v[128:131], v[58:61]
	v_mfma_f32_16x16x32_bf16 v[50:53], v[70:73], v[128:131], v[66:69]
	s_waitcnt lgkmcnt(1)
	v_mfma_f32_16x16x32_bf16 v[10:13], v[78:81], v[128:131], v[10:13]
	ds_read_b128 v[18:21], v9 offset:4480
	ds_read_b128 v[58:61], v9 offset:192
	s_waitcnt lgkmcnt(2)
	v_mfma_f32_16x16x32_bf16 v[14:17], v[54:57], v[132:135], v[14:17]
	ds_read_b128 v[54:57], v9 offset:8832
	ds_read_b128 v[62:65], v9 offset:4544
	s_waitcnt lgkmcnt(3)
	v_mfma_f32_16x16x32_bf16 v[18:21], v[18:21], v[132:135], v[22:25]
	s_nop 2
	ds_read_b128 v[22:25], v9 offset:13184
	ds_read_b128 v[66:69], v9 offset:8896
	s_waitcnt lgkmcnt(3)
	v_mfma_f32_16x16x32_bf16 v[26:29], v[54:57], v[132:135], v[26:29]
	ds_read_b128 v[54:57], v9 offset:17536
	ds_read_b128 v[70:73], v9 offset:13248
	s_waitcnt lgkmcnt(3)
	v_mfma_f32_16x16x32_bf16 v[22:25], v[22:25], v[132:135], v[30:33]
	s_nop 2
	ds_read_b128 v[30:33], v9 offset:21888
	ds_read_b128 v[74:77], v9 offset:17600
	s_waitcnt lgkmcnt(3)
	v_mfma_f32_16x16x32_bf16 v[34:37], v[54:57], v[132:135], v[34:37]
	ds_read_b128 v[54:57], v9 offset:26240
	ds_read_b128 v[78:81], v9 offset:21952
	ds_read_b128 v[82:85], v9 offset:26304
	s_waitcnt lgkmcnt(4)
	v_mfma_f32_16x16x32_bf16 v[30:33], v[30:33], v[132:135], v[42:45]
	s_nop 2
	ds_read_b128 v[42:45], v9 offset:30592
	v_mfma_f32_16x16x32_bf16 v[14:17], v[58:61], v[136:139], v[14:17]
	s_waitcnt lgkmcnt(3)
	v_mfma_f32_16x16x32_bf16 v[50:53], v[54:57], v[132:135], v[50:53]
	ds_read_b128 v[54:57], v9 offset:30656
	s_nop 4
	v_cvt_pk_bf16_f32 v14, v14, v15
	v_cvt_pk_bf16_f32 v15, v16, v17
	s_waitcnt lgkmcnt(1)
	v_mfma_f32_16x16x32_bf16 v[10:13], v[42:45], v[132:135], v[10:13]
	v_lshlrev_b64 v[38:39], 11, v[88:89]
	v_lshl_add_u64 v[38:39], v[86:87], 0, v[38:39]
	global_store_dwordx2 v[38:39], v[14:15], off
	v_mfma_f32_16x16x32_bf16 v[14:17], v[62:65], v[136:139], v[18:21]
	s_waitcnt lgkmcnt(0)
	v_mfma_f32_16x16x32_bf16 v[10:13], v[54:57], v[136:139], v[10:13]
	s_nop 5
	v_cvt_pk_bf16_f32 v14, v14, v15
	v_cvt_pk_bf16_f32 v15, v16, v17
	global_store_dwordx2 v[38:39], v[14:15], off offset:32
	v_mfma_f32_16x16x32_bf16 v[14:17], v[66:69], v[136:139], v[26:29]
	v_cvt_pk_bf16_f32 v10, v10, v11
	v_cvt_pk_bf16_f32 v11, v12, v13
	global_store_dwordx2 v[38:39], v[10:11], off offset:224
	s_nop 4
	v_cvt_pk_bf16_f32 v14, v14, v15
	v_cvt_pk_bf16_f32 v15, v16, v17
	global_store_dwordx2 v[38:39], v[14:15], off offset:64
	v_mfma_f32_16x16x32_bf16 v[14:17], v[70:73], v[136:139], v[22:25]
	s_nop 7
	v_cvt_pk_bf16_f32 v14, v14, v15
	v_cvt_pk_bf16_f32 v15, v16, v17
	global_store_dwordx2 v[38:39], v[14:15], off offset:96
	v_mfma_f32_16x16x32_bf16 v[14:17], v[74:77], v[136:139], v[34:37]
	s_nop 7
	v_cvt_pk_bf16_f32 v14, v14, v15
	v_cvt_pk_bf16_f32 v15, v16, v17
	global_store_dwordx2 v[38:39], v[14:15], off offset:128
	v_mfma_f32_16x16x32_bf16 v[14:17], v[78:81], v[136:139], v[30:33]
	s_nop 7
	v_cvt_pk_bf16_f32 v14, v14, v15
	v_cvt_pk_bf16_f32 v15, v16, v17
	global_store_dwordx2 v[38:39], v[14:15], off offset:160
	v_mfma_f32_16x16x32_bf16 v[14:17], v[82:85], v[136:139], v[50:53]
	s_nop 7
	v_cvt_pk_bf16_f32 v14, v14, v15
	v_cvt_pk_bf16_f32 v15, v16, v17
	global_store_dwordx2 v[38:39], v[14:15], off offset:192
	s_branch .LBB0_758
